# scan: next chunk's LDS buffer addresses computed in the previous chunk's tail (under the y-store latency); chunk entry starts with the reads
# baseline (speedup 1.0000x reference)
; __device__ __forceinline__ void phase_scan(KP p) {
;     ...
;       } else if (c >= 0) {
;         const int buf = c & 1;
;         const float* fbase = feat + (buf * 32) * 320 + cs * 4;
;         const float* vb4 = vbuf + (buf * 16 + rowl) * 32;
;         const bool b3 = (cs & 8) != 0, b2 = (cs & 4) != 0;
;         float* yb = ybuf + (buf * 32 + (b3 ? 2 : 0) + (b2 ? 1 : 0)) * 16 + rowl;
;         float4 Ar, Aw, Ak, An, Ab, Br, Bw, Bk, Bn, Bb, Cr, Cw, Ck, Cn, Cb, Dr, Dw, Dk, Dn, Db;
;         float4 vcur = *(const float4*)vb4, vnext;
;         float q0 = 0.f, q1 = 0.f, q2 = 0.f, q3 = 0.f, p0 = 0.f, p1 = 0.f, p2 = 0.f, p3 = 0.f;
.Lscan_entry:
	s_and_b32 s70, s18, 1
	s_cmp_lg_u32 s18, 0
	s_cbranch_scc1 .Lscan_hot
	v_and_b32_e32 v93, 63, v135
	v_bfe_u32 v94, v93, 3, 2
	v_and_b32_e32 v95, 3, v93
	v_lshl_add_u32 v94, v94, 2, v95
	v_lshrrev_b32_e32 v95, 5, v93
	v_lshl_add_u32 v94, v94, 1, v95
	s_mov_b32 s19, 0x16000
	v_lshl_add_u32 v129, v94, 4, s19
	v_and_b32_e32 v94, 15, v93
	v_lshlrev_b32_e32 v95, 3, v95
	v_sub_u32_e32 v94, v94, v95
	v_and_b32_e32 v95, 1, v94
	v_lshlrev_b32_e32 v95, 4, v95
	v_mov_b32_e32 v93, 0x3f80
	v_lshlrev_b32_e32 v93, v95, v93
	v_lshrrev_b32_e32 v94, 1, v94
	v_cmp_eq_u32_e64 s[74:75], 0, v94
	s_nop 1
	v_cndmask_b32_e64 v124, 0, v93, s[74:75]
	v_cmp_eq_u32_e64 s[74:75], 1, v94
	s_nop 1
	v_cndmask_b32_e64 v125, 0, v93, s[74:75]
	v_cmp_eq_u32_e64 s[74:75], 2, v94
	s_nop 1
	v_cndmask_b32_e64 v126, 0, v93, s[74:75]
	v_cmp_eq_u32_e64 s[74:75], 3, v94
	s_nop 1
	v_cndmask_b32_e64 v127, 0, v93, s[74:75]
	s_mul_i32 s19, s70, 0x4400
	v_add_u32_e32 v128, s19, v129
	s_mul_i32 s19, s70, 0xa000
	v_lshl_add_u32 v106, s70, 11, v121
	v_add_u32_e32 v105, s19, v120
	v_lshl_add_u32 v107, s70, 11, v146
.Lscan_hot:
	ds_read_b128 v[108:111], v128
	ds_read_b128 v[112:115], v128 offset:544
	ds_read_b128 v[80:83], v106
	ds_read_b128 v[16:19], v105 offset:256
	ds_read_b128 v[36:39], v105 offset:1536
	s_waitcnt lgkmcnt(4)
	v_mfma_f32_32x32x16_bf16 v[0:15], v[108:111], v[124:127], 0
	s_waitcnt lgkmcnt(3)
	v_mfma_f32_32x32x16_bf16 v[20:35], v[112:115], v[124:127], 0
	ds_read_b128 v[108:111], v128 offset:1088
	s_nop 7
	s_nop 3
	s_waitcnt lgkmcnt(2)
	v_pk_mul_f32 v[84:85], v[116:117], v[8:9]
	v_pk_mul_f32 v[86:87], v[80:81], v[4:5] op_sel_hi:[0,1]
	v_pk_fma_f32 v[84:85], v[118:119], v[10:11], v[84:85]
	v_pk_mul_f32 v[88:89], v[80:81], v[6:7] op_sel_hi:[0,1]
	v_add_f32_e32 v92, v84, v85
	v_pk_fma_f32 v[86:87], v[116:117], v[16:17], v[86:87]
	ds_read_b128 v[112:115], v128 offset:1632
	v_add_f32_dpp v92, v92, v92 quad_perm:[1,0,3,2] row_mask:0xf bank_mask:0xf bound_ctrl:1
	v_pk_fma_f32 v[88:89], v[118:119], v[18:19], v[88:89]
	s_waitcnt lgkmcnt(1)
	v_mfma_f32_32x32x16_bf16 v[40:55], v[108:111], v[124:127], 0
	v_add_f32_dpp v92, v92, v92 quad_perm:[2,3,0,1] row_mask:0xf bank_mask:0xf bound_ctrl:1
	s_nop 1
	v_add_f32_dpp v92, v92, v92 row_half_mirror row_mask:0xf bank_mask:0xf bound_ctrl:1
	ds_read_b128 v[56:59], v105 offset:2816
	s_nop 0
	v_add_f32_dpp v92, v92, v92 row_mirror row_mask:0xf bank_mask:0xf bound_ctrl:1
	v_pk_fma_f32 v[116:117], v[12:13], v[92:93], v[86:87] op_sel_hi:[1,0,1]
	v_pk_fma_f32 v[118:119], v[14:15], v[92:93], v[88:89] op_sel_hi:[1,0,1]
	v_pk_mul_f32 v[84:85], v[116:117], v[28:29]
	v_pk_mul_f32 v[86:87], v[80:81], v[24:25] op_sel:[1,0]
	v_pk_fma_f32 v[84:85], v[118:119], v[30:31], v[84:85]
	v_pk_mul_f32 v[88:89], v[80:81], v[26:27] op_sel:[1,0]
	v_add_f32_e32 v92, v84, v85
	v_pk_fma_f32 v[86:87], v[116:117], v[36:37], v[86:87]
	v_pk_mul_f32 v[90:91], v[116:117], v[0:1]
	v_add_f32_dpp v92, v92, v92 quad_perm:[1,0,3,2] row_mask:0xf bank_mask:0xf bound_ctrl:1
	v_pk_fma_f32 v[88:89], v[118:119], v[38:39], v[88:89]
	v_pk_fma_f32 v[90:91], v[118:119], v[2:3], v[90:91]
	s_waitcnt lgkmcnt(1)
	v_mfma_f32_32x32x16_bf16 v[60:75], v[112:115], v[124:127], 0
	v_add_f32_dpp v92, v92, v92 quad_perm:[2,3,0,1] row_mask:0xf bank_mask:0xf bound_ctrl:1
	v_add_f32_e32 v96, v90, v91
	ds_read_b128 v[108:111], v128 offset:2176
	v_add_f32_dpp v92, v92, v92 row_half_mirror row_mask:0xf bank_mask:0xf bound_ctrl:1
	ds_read_b128 v[76:79], v105 offset:4096
	s_nop 0
	v_add_f32_dpp v92, v92, v92 row_mirror row_mask:0xf bank_mask:0xf bound_ctrl:1
	v_pk_fma_f32 v[116:117], v[32:33], v[92:93], v[86:87] op_sel_hi:[1,0,1]
	v_pk_fma_f32 v[118:119], v[34:35], v[92:93], v[88:89] op_sel_hi:[1,0,1]
	s_waitcnt lgkmcnt(2)
	v_pk_mul_f32 v[84:85], v[116:117], v[48:49]
	v_pk_mul_f32 v[86:87], v[82:83], v[44:45] op_sel_hi:[0,1]
	v_pk_fma_f32 v[84:85], v[118:119], v[50:51], v[84:85]
	v_pk_mul_f32 v[88:89], v[82:83], v[46:47] op_sel_hi:[0,1]
	v_add_f32_e32 v92, v84, v85
	v_pk_fma_f32 v[86:87], v[116:117], v[56:57], v[86:87]
	v_pk_mul_f32 v[90:91], v[116:117], v[20:21]
	v_add_f32_dpp v92, v92, v92 quad_perm:[1,0,3,2] row_mask:0xf bank_mask:0xf bound_ctrl:1
	v_pk_fma_f32 v[88:89], v[118:119], v[58:59], v[88:89]
	v_pk_fma_f32 v[90:91], v[118:119], v[22:23], v[90:91]
	s_waitcnt lgkmcnt(1)
	v_mfma_f32_32x32x16_bf16 v[0:15], v[108:111], v[124:127], 0
	v_add_f32_dpp v92, v92, v92 quad_perm:[2,3,0,1] row_mask:0xf bank_mask:0xf bound_ctrl:1
	v_add_f32_e32 v97, v90, v91
	ds_read_b128 v[112:115], v128 offset:2720
	v_add_f32_dpp v92, v92, v92 row_half_mirror row_mask:0xf bank_mask:0xf bound_ctrl:1
	ds_read_b128 v[16:19], v105 offset:5376
	s_nop 0
	v_add_f32_dpp v92, v92, v92 row_mirror row_mask:0xf bank_mask:0xf bound_ctrl:1
	v_pk_fma_f32 v[116:117], v[52:53], v[92:93], v[86:87] op_sel_hi:[1,0,1]
	v_pk_fma_f32 v[118:119], v[54:55], v[92:93], v[88:89] op_sel_hi:[1,0,1]
	s_waitcnt lgkmcnt(2)
	v_pk_mul_f32 v[84:85], v[116:117], v[68:69]
	v_pk_mul_f32 v[86:87], v[82:83], v[64:65] op_sel:[1,0]
	v_pk_fma_f32 v[84:85], v[118:119], v[70:71], v[84:85]
	v_pk_mul_f32 v[88:89], v[82:83], v[66:67] op_sel:[1,0]
	ds_read_b128 v[80:83], v106 offset:16
	v_add_f32_e32 v92, v84, v85
	v_pk_fma_f32 v[86:87], v[116:117], v[76:77], v[86:87]
	v_pk_mul_f32 v[90:91], v[116:117], v[40:41]
	v_add_f32_dpp v92, v92, v92 quad_perm:[1,0,3,2] row_mask:0xf bank_mask:0xf bound_ctrl:1
	v_pk_fma_f32 v[88:89], v[118:119], v[78:79], v[88:89]
	v_pk_fma_f32 v[90:91], v[118:119], v[42:43], v[90:91]
	s_waitcnt lgkmcnt(2)
; #define YRED4(dst) { \
;           float a0 = b3 ? p2 : p0, a1 = b3 ? p3 : p1; const float s0 = b3 ? p0 : p2, s1 = b3 ? p1 : p3; \
;           a0 += dppf<0x128>(s0); a1 += dppf<0x128>(s1); \
;           float cc = b2 ? a1 : a0; const float dd = b2 ? a0 : a1; \
;           cc += dppf<0x141>(dd); cc += dppf<0xB1>(cc); cc += dppf<0x4E>(cc); dst = cc; }
; __device__ __forceinline__ void phase_scan(KP p) {
;     ...
;           SLD(C, st + 2); vnext = *(const float4*)(vb4 + st + 4);
;           __builtin_amdgcn_sched_barrier(0);
;           if (g > 0) { float yv; YRED4(yv); yb[(st - 4) * 16] = yv; }
;           SCOMP(A, vcur.x, q0);
;           SLD(D, st + 3);
;           __builtin_amdgcn_sched_barrier(0);
;           SCOMP(B, vcur.y, q1);
;           SLD(A, st + 4);
;           __builtin_amdgcn_sched_barrier(0);
;           SCOMP(C, vcur.z, q2);
;           SLD(B, st + 5);
;           __builtin_amdgcn_sched_barrier(0);
;           SCOMP(D, vcur.w, q3);
;           vcur = vnext; p0 = q0; p1 = q1; p2 = q2; p3 = q3;
	v_mfma_f32_32x32x16_bf16 v[20:35], v[112:115], v[124:127], 0
	v_add_f32_dpp v92, v92, v92 quad_perm:[2,3,0,1] row_mask:0xf bank_mask:0xf bound_ctrl:1
	v_add_f32_e32 v98, v90, v91
	ds_read_b128 v[108:111], v128 offset:3264
	v_add_f32_dpp v92, v92, v92 row_half_mirror row_mask:0xf bank_mask:0xf bound_ctrl:1
	ds_read_b128 v[36:39], v105 offset:6656
	s_nop 0
	v_add_f32_dpp v92, v92, v92 row_mirror row_mask:0xf bank_mask:0xf bound_ctrl:1
	v_pk_fma_f32 v[116:117], v[72:73], v[92:93], v[86:87] op_sel_hi:[1,0,1]
	v_pk_fma_f32 v[118:119], v[74:75], v[92:93], v[88:89] op_sel_hi:[1,0,1]
	s_waitcnt lgkmcnt(2)
	v_pk_mul_f32 v[84:85], v[116:117], v[8:9]
	v_pk_mul_f32 v[86:87], v[80:81], v[4:5] op_sel_hi:[0,1]
	v_pk_fma_f32 v[84:85], v[118:119], v[10:11], v[84:85]
	v_pk_mul_f32 v[88:89], v[80:81], v[6:7] op_sel_hi:[0,1]
	v_add_f32_e32 v92, v84, v85
	v_pk_fma_f32 v[86:87], v[116:117], v[16:17], v[86:87]
	v_pk_mul_f32 v[90:91], v[116:117], v[60:61]
	v_add_f32_dpp v92, v92, v92 quad_perm:[1,0,3,2] row_mask:0xf bank_mask:0xf bound_ctrl:1
	v_pk_fma_f32 v[88:89], v[118:119], v[18:19], v[88:89]
	v_pk_fma_f32 v[90:91], v[118:119], v[62:63], v[90:91]
	s_waitcnt lgkmcnt(1)
	v_mfma_f32_32x32x16_bf16 v[40:55], v[108:111], v[124:127], 0
	v_add_f32_dpp v92, v92, v92 quad_perm:[2,3,0,1] row_mask:0xf bank_mask:0xf bound_ctrl:1
	v_add_f32_e32 v99, v90, v91
	ds_read_b128 v[112:115], v128 offset:3808
	v_cndmask_b32_e64 v100, v98, v96, s[38:39]
	v_cndmask_b32_e64 v102, v96, v98, s[38:39]
	v_add_f32_dpp v92, v92, v92 row_half_mirror row_mask:0xf bank_mask:0xf bound_ctrl:1
	ds_read_b128 v[56:59], v105 offset:7936
	v_cndmask_b32_e64 v101, v99, v97, s[38:39]
	v_cndmask_b32_e64 v103, v97, v99, s[38:39]
	v_add_f32_dpp v92, v92, v92 row_mirror row_mask:0xf bank_mask:0xf bound_ctrl:1
	v_pk_fma_f32 v[116:117], v[12:13], v[92:93], v[86:87] op_sel_hi:[1,0,1]
	v_pk_fma_f32 v[118:119], v[14:15], v[92:93], v[88:89] op_sel_hi:[1,0,1]
	s_waitcnt lgkmcnt(2)
	v_pk_mul_f32 v[84:85], v[116:117], v[28:29]
	v_pk_mul_f32 v[86:87], v[80:81], v[24:25] op_sel:[1,0]
	v_pk_fma_f32 v[84:85], v[118:119], v[30:31], v[84:85]
	v_pk_mul_f32 v[88:89], v[80:81], v[26:27] op_sel:[1,0]
	v_add_f32_e32 v92, v84, v85
	v_pk_fma_f32 v[86:87], v[116:117], v[36:37], v[86:87]
	v_pk_mul_f32 v[90:91], v[116:117], v[0:1]
	v_add_f32_dpp v92, v92, v92 quad_perm:[1,0,3,2] row_mask:0xf bank_mask:0xf bound_ctrl:1
	v_pk_fma_f32 v[88:89], v[118:119], v[38:39], v[88:89]
	v_pk_fma_f32 v[90:91], v[118:119], v[2:3], v[90:91]
	s_waitcnt lgkmcnt(1)
	v_mfma_f32_32x32x16_bf16 v[60:75], v[112:115], v[124:127], 0
	v_add_f32_dpp v92, v92, v92 quad_perm:[2,3,0,1] row_mask:0xf bank_mask:0xf bound_ctrl:1
	v_add_f32_e32 v96, v90, v91
	ds_read_b128 v[108:111], v128 offset:4352
	v_add_f32_dpp v102, v102, v100 row_ror:8 row_mask:0xf bank_mask:0xf bound_ctrl:1
	v_add_f32_dpp v92, v92, v92 row_half_mirror row_mask:0xf bank_mask:0xf bound_ctrl:1
	ds_read_b128 v[76:79], v105 offset:9216
	v_add_f32_dpp v103, v103, v101 row_ror:8 row_mask:0xf bank_mask:0xf bound_ctrl:1
	v_add_f32_dpp v92, v92, v92 row_mirror row_mask:0xf bank_mask:0xf bound_ctrl:1
	v_cndmask_b32_e64 v104, v103, v102, s[40:41]
	v_cndmask_b32_e64 v102, v102, v103, s[40:41]
	v_pk_fma_f32 v[116:117], v[32:33], v[92:93], v[86:87] op_sel_hi:[1,0,1]
	v_pk_fma_f32 v[118:119], v[34:35], v[92:93], v[88:89] op_sel_hi:[1,0,1]
	s_waitcnt lgkmcnt(2)
	v_pk_mul_f32 v[84:85], v[116:117], v[48:49]
	v_pk_mul_f32 v[86:87], v[82:83], v[44:45] op_sel_hi:[0,1]
	v_pk_fma_f32 v[84:85], v[118:119], v[50:51], v[84:85]
	v_pk_mul_f32 v[88:89], v[82:83], v[46:47] op_sel_hi:[0,1]
	v_add_f32_e32 v92, v84, v85
	v_pk_fma_f32 v[86:87], v[116:117], v[56:57], v[86:87]
	v_pk_mul_f32 v[90:91], v[116:117], v[20:21]
	v_add_f32_dpp v92, v92, v92 quad_perm:[1,0,3,2] row_mask:0xf bank_mask:0xf bound_ctrl:1
	v_pk_fma_f32 v[88:89], v[118:119], v[58:59], v[88:89]
	v_pk_fma_f32 v[90:91], v[118:119], v[22:23], v[90:91]
	s_waitcnt lgkmcnt(1)
	v_mfma_f32_32x32x16_bf16 v[0:15], v[108:111], v[124:127], 0
	v_add_f32_dpp v92, v92, v92 quad_perm:[2,3,0,1] row_mask:0xf bank_mask:0xf bound_ctrl:1
	v_add_f32_e32 v97, v90, v91
	ds_read_b128 v[112:115], v128 offset:4896
	v_add_f32_dpp v92, v92, v92 row_half_mirror row_mask:0xf bank_mask:0xf bound_ctrl:1
	ds_read_b128 v[16:19], v105 offset:10496
	v_add_f32_dpp v102, v102, v104 row_half_mirror row_mask:0xf bank_mask:0xf bound_ctrl:1
	v_add_f32_dpp v92, v92, v92 row_mirror row_mask:0xf bank_mask:0xf bound_ctrl:1
	v_pk_fma_f32 v[116:117], v[52:53], v[92:93], v[86:87] op_sel_hi:[1,0,1]
	v_pk_fma_f32 v[118:119], v[54:55], v[92:93], v[88:89] op_sel_hi:[1,0,1]
	v_add_f32_dpp v102, v102, v102 quad_perm:[1,0,3,2] row_mask:0xf bank_mask:0xf bound_ctrl:1
	s_waitcnt lgkmcnt(2)
	v_pk_mul_f32 v[84:85], v[116:117], v[68:69]
	v_pk_mul_f32 v[86:87], v[82:83], v[64:65] op_sel:[1,0]
	v_pk_fma_f32 v[84:85], v[118:119], v[70:71], v[84:85]
	v_pk_mul_f32 v[88:89], v[82:83], v[66:67] op_sel:[1,0]
	ds_read_b128 v[80:83], v106 offset:32
	v_add_f32_e32 v92, v84, v85
	v_pk_fma_f32 v[86:87], v[116:117], v[76:77], v[86:87]
	v_pk_mul_f32 v[90:91], v[116:117], v[40:41]
	v_add_f32_dpp v92, v92, v92 quad_perm:[1,0,3,2] row_mask:0xf bank_mask:0xf bound_ctrl:1
	v_pk_fma_f32 v[88:89], v[118:119], v[78:79], v[88:89]
	v_pk_fma_f32 v[90:91], v[118:119], v[42:43], v[90:91]
	s_waitcnt lgkmcnt(2)
; #define YRED4(dst) { \
;           float a0 = b3 ? p2 : p0, a1 = b3 ? p3 : p1; const float s0 = b3 ? p0 : p2, s1 = b3 ? p1 : p3; \
;           a0 += dppf<0x128>(s0); a1 += dppf<0x128>(s1); \
;           float cc = b2 ? a1 : a0; const float dd = b2 ? a0 : a1; \
;           cc += dppf<0x141>(dd); cc += dppf<0xB1>(cc); cc += dppf<0x4E>(cc); dst = cc; }
; __device__ __forceinline__ void phase_scan(KP p) {
;     ...
;         for (int g = 0; g < 8; ++g) {
;           const int st = g * 4;
;           SLD(C, st + 2); vnext = *(const float4*)(vb4 + st + 4);
;           __builtin_amdgcn_sched_barrier(0);
;           if (g > 0) { float yv; YRED4(yv); yb[(st - 4) * 16] = yv; }
;           SCOMP(A, vcur.x, q0);
;           SLD(D, st + 3);
;           __builtin_amdgcn_sched_barrier(0);
;           SCOMP(B, vcur.y, q1);
;           SLD(A, st + 4);
;           __builtin_amdgcn_sched_barrier(0);
;           SCOMP(C, vcur.z, q2);
;           SLD(B, st + 5);
;           __builtin_amdgcn_sched_barrier(0);
;           SCOMP(D, vcur.w, q3);
;           vcur = vnext; p0 = q0; p1 = q1; p2 = q2; p3 = q3;
	v_mfma_f32_32x32x16_bf16 v[20:35], v[112:115], v[124:127], 0
	v_add_f32_dpp v92, v92, v92 quad_perm:[2,3,0,1] row_mask:0xf bank_mask:0xf bound_ctrl:1
	v_add_f32_e32 v98, v90, v91
	ds_read_b128 v[108:111], v128 offset:5440
	v_add_f32_dpp v92, v92, v92 row_half_mirror row_mask:0xf bank_mask:0xf bound_ctrl:1
	ds_read_b128 v[36:39], v105 offset:11776
	v_add_f32_dpp v102, v102, v102 quad_perm:[2,3,0,1] row_mask:0xf bank_mask:0xf bound_ctrl:1
	v_add_f32_dpp v92, v92, v92 row_mirror row_mask:0xf bank_mask:0xf bound_ctrl:1
	v_pk_fma_f32 v[116:117], v[72:73], v[92:93], v[86:87] op_sel_hi:[1,0,1]
	v_pk_fma_f32 v[118:119], v[74:75], v[92:93], v[88:89] op_sel_hi:[1,0,1]
	ds_write_b32 v107, v102
	s_waitcnt lgkmcnt(3)
	v_pk_mul_f32 v[84:85], v[116:117], v[8:9]
	v_pk_mul_f32 v[86:87], v[80:81], v[4:5] op_sel_hi:[0,1]
	v_pk_fma_f32 v[84:85], v[118:119], v[10:11], v[84:85]
	v_pk_mul_f32 v[88:89], v[80:81], v[6:7] op_sel_hi:[0,1]
	v_add_f32_e32 v92, v84, v85
	v_pk_fma_f32 v[86:87], v[116:117], v[16:17], v[86:87]
	v_pk_mul_f32 v[90:91], v[116:117], v[60:61]
	v_add_f32_dpp v92, v92, v92 quad_perm:[1,0,3,2] row_mask:0xf bank_mask:0xf bound_ctrl:1
	v_pk_fma_f32 v[88:89], v[118:119], v[18:19], v[88:89]
	v_pk_fma_f32 v[90:91], v[118:119], v[62:63], v[90:91]
	s_waitcnt lgkmcnt(2)
	v_mfma_f32_32x32x16_bf16 v[40:55], v[108:111], v[124:127], 0
	v_add_f32_dpp v92, v92, v92 quad_perm:[2,3,0,1] row_mask:0xf bank_mask:0xf bound_ctrl:1
	v_add_f32_e32 v99, v90, v91
	ds_read_b128 v[112:115], v128 offset:5984
	v_cndmask_b32_e64 v100, v98, v96, s[38:39]
	v_cndmask_b32_e64 v102, v96, v98, s[38:39]
	v_add_f32_dpp v92, v92, v92 row_half_mirror row_mask:0xf bank_mask:0xf bound_ctrl:1
	ds_read_b128 v[56:59], v105 offset:13056
	v_cndmask_b32_e64 v101, v99, v97, s[38:39]
	v_cndmask_b32_e64 v103, v97, v99, s[38:39]
	v_add_f32_dpp v92, v92, v92 row_mirror row_mask:0xf bank_mask:0xf bound_ctrl:1
	v_pk_fma_f32 v[116:117], v[12:13], v[92:93], v[86:87] op_sel_hi:[1,0,1]
	v_pk_fma_f32 v[118:119], v[14:15], v[92:93], v[88:89] op_sel_hi:[1,0,1]
	s_waitcnt lgkmcnt(3)
	v_pk_mul_f32 v[84:85], v[116:117], v[28:29]
	v_pk_mul_f32 v[86:87], v[80:81], v[24:25] op_sel:[1,0]
	v_pk_fma_f32 v[84:85], v[118:119], v[30:31], v[84:85]
	v_pk_mul_f32 v[88:89], v[80:81], v[26:27] op_sel:[1,0]
	v_add_f32_e32 v92, v84, v85
	v_pk_fma_f32 v[86:87], v[116:117], v[36:37], v[86:87]
	v_pk_mul_f32 v[90:91], v[116:117], v[0:1]
	v_add_f32_dpp v92, v92, v92 quad_perm:[1,0,3,2] row_mask:0xf bank_mask:0xf bound_ctrl:1
	v_pk_fma_f32 v[88:89], v[118:119], v[38:39], v[88:89]
	v_pk_fma_f32 v[90:91], v[118:119], v[2:3], v[90:91]
	s_waitcnt lgkmcnt(1)
	v_mfma_f32_32x32x16_bf16 v[60:75], v[112:115], v[124:127], 0
	v_add_f32_dpp v92, v92, v92 quad_perm:[2,3,0,1] row_mask:0xf bank_mask:0xf bound_ctrl:1
	v_add_f32_e32 v96, v90, v91
	ds_read_b128 v[108:111], v128 offset:6528
	v_add_f32_dpp v102, v102, v100 row_ror:8 row_mask:0xf bank_mask:0xf bound_ctrl:1
	v_add_f32_dpp v92, v92, v92 row_half_mirror row_mask:0xf bank_mask:0xf bound_ctrl:1
	ds_read_b128 v[76:79], v105 offset:14336
	v_add_f32_dpp v103, v103, v101 row_ror:8 row_mask:0xf bank_mask:0xf bound_ctrl:1
	v_add_f32_dpp v92, v92, v92 row_mirror row_mask:0xf bank_mask:0xf bound_ctrl:1
	v_cndmask_b32_e64 v104, v103, v102, s[40:41]
	v_cndmask_b32_e64 v102, v102, v103, s[40:41]
	v_pk_fma_f32 v[116:117], v[32:33], v[92:93], v[86:87] op_sel_hi:[1,0,1]
	v_pk_fma_f32 v[118:119], v[34:35], v[92:93], v[88:89] op_sel_hi:[1,0,1]
	s_waitcnt lgkmcnt(2)
	v_pk_mul_f32 v[84:85], v[116:117], v[48:49]
	v_pk_mul_f32 v[86:87], v[82:83], v[44:45] op_sel_hi:[0,1]
	v_pk_fma_f32 v[84:85], v[118:119], v[50:51], v[84:85]
	v_pk_mul_f32 v[88:89], v[82:83], v[46:47] op_sel_hi:[0,1]
	v_add_f32_e32 v92, v84, v85
	v_pk_fma_f32 v[86:87], v[116:117], v[56:57], v[86:87]
	v_pk_mul_f32 v[90:91], v[116:117], v[20:21]
	v_add_f32_dpp v92, v92, v92 quad_perm:[1,0,3,2] row_mask:0xf bank_mask:0xf bound_ctrl:1
	v_pk_fma_f32 v[88:89], v[118:119], v[58:59], v[88:89]
	v_pk_fma_f32 v[90:91], v[118:119], v[22:23], v[90:91]
	s_waitcnt lgkmcnt(1)
	v_mfma_f32_32x32x16_bf16 v[0:15], v[108:111], v[124:127], 0
	v_add_f32_dpp v92, v92, v92 quad_perm:[2,3,0,1] row_mask:0xf bank_mask:0xf bound_ctrl:1
	v_add_f32_e32 v97, v90, v91
	ds_read_b128 v[112:115], v128 offset:7072
	v_add_f32_dpp v92, v92, v92 row_half_mirror row_mask:0xf bank_mask:0xf bound_ctrl:1
	ds_read_b128 v[16:19], v105 offset:15616
	v_add_f32_dpp v102, v102, v104 row_half_mirror row_mask:0xf bank_mask:0xf bound_ctrl:1
	v_add_f32_dpp v92, v92, v92 row_mirror row_mask:0xf bank_mask:0xf bound_ctrl:1
	v_pk_fma_f32 v[116:117], v[52:53], v[92:93], v[86:87] op_sel_hi:[1,0,1]
	v_pk_fma_f32 v[118:119], v[54:55], v[92:93], v[88:89] op_sel_hi:[1,0,1]
	v_add_f32_dpp v102, v102, v102 quad_perm:[1,0,3,2] row_mask:0xf bank_mask:0xf bound_ctrl:1
	s_waitcnt lgkmcnt(2)
	v_pk_mul_f32 v[84:85], v[116:117], v[68:69]
	v_pk_mul_f32 v[86:87], v[82:83], v[64:65] op_sel:[1,0]
	v_pk_fma_f32 v[84:85], v[118:119], v[70:71], v[84:85]
	v_pk_mul_f32 v[88:89], v[82:83], v[66:67] op_sel:[1,0]
	ds_read_b128 v[80:83], v106 offset:48
	v_add_f32_e32 v92, v84, v85
	v_pk_fma_f32 v[86:87], v[116:117], v[76:77], v[86:87]
	v_pk_mul_f32 v[90:91], v[116:117], v[40:41]
	v_add_f32_dpp v92, v92, v92 quad_perm:[1,0,3,2] row_mask:0xf bank_mask:0xf bound_ctrl:1
	v_pk_fma_f32 v[88:89], v[118:119], v[78:79], v[88:89]
	v_pk_fma_f32 v[90:91], v[118:119], v[42:43], v[90:91]
	s_waitcnt lgkmcnt(2)
; #define YRED4(dst) { \
;           float a0 = b3 ? p2 : p0, a1 = b3 ? p3 : p1; const float s0 = b3 ? p0 : p2, s1 = b3 ? p1 : p3; \
;           a0 += dppf<0x128>(s0); a1 += dppf<0x128>(s1); \
;           float cc = b2 ? a1 : a0; const float dd = b2 ? a0 : a1; \
;           cc += dppf<0x141>(dd); cc += dppf<0xB1>(cc); cc += dppf<0x4E>(cc); dst = cc; }
; __device__ __forceinline__ void phase_scan(KP p) {
;     ...
;         for (int g = 0; g < 8; ++g) {
;           const int st = g * 4;
;           SLD(C, st + 2); vnext = *(const float4*)(vb4 + st + 4);
;           __builtin_amdgcn_sched_barrier(0);
;           if (g > 0) { float yv; YRED4(yv); yb[(st - 4) * 16] = yv; }
;           SCOMP(A, vcur.x, q0);
;           SLD(D, st + 3);
;           __builtin_amdgcn_sched_barrier(0);
;           SCOMP(B, vcur.y, q1);
;           SLD(A, st + 4);
;           __builtin_amdgcn_sched_barrier(0);
;           SCOMP(C, vcur.z, q2);
;           SLD(B, st + 5);
;           __builtin_amdgcn_sched_barrier(0);
;           SCOMP(D, vcur.w, q3);
;           vcur = vnext; p0 = q0; p1 = q1; p2 = q2; p3 = q3;
	v_mfma_f32_32x32x16_bf16 v[20:35], v[112:115], v[124:127], 0
	v_add_f32_dpp v92, v92, v92 quad_perm:[2,3,0,1] row_mask:0xf bank_mask:0xf bound_ctrl:1
	v_add_f32_e32 v98, v90, v91
	ds_read_b128 v[108:111], v128 offset:7616
	v_add_f32_dpp v92, v92, v92 row_half_mirror row_mask:0xf bank_mask:0xf bound_ctrl:1
	ds_read_b128 v[36:39], v105 offset:16896
	v_add_f32_dpp v102, v102, v102 quad_perm:[2,3,0,1] row_mask:0xf bank_mask:0xf bound_ctrl:1
	v_add_f32_dpp v92, v92, v92 row_mirror row_mask:0xf bank_mask:0xf bound_ctrl:1
	v_pk_fma_f32 v[116:117], v[72:73], v[92:93], v[86:87] op_sel_hi:[1,0,1]
	v_pk_fma_f32 v[118:119], v[74:75], v[92:93], v[88:89] op_sel_hi:[1,0,1]
	ds_write_b32 v107, v102 offset:256
	s_waitcnt lgkmcnt(3)
	v_pk_mul_f32 v[84:85], v[116:117], v[8:9]
	v_pk_mul_f32 v[86:87], v[80:81], v[4:5] op_sel_hi:[0,1]
	v_pk_fma_f32 v[84:85], v[118:119], v[10:11], v[84:85]
	v_pk_mul_f32 v[88:89], v[80:81], v[6:7] op_sel_hi:[0,1]
	v_add_f32_e32 v92, v84, v85
	v_pk_fma_f32 v[86:87], v[116:117], v[16:17], v[86:87]
	v_pk_mul_f32 v[90:91], v[116:117], v[60:61]
	v_add_f32_dpp v92, v92, v92 quad_perm:[1,0,3,2] row_mask:0xf bank_mask:0xf bound_ctrl:1
	v_pk_fma_f32 v[88:89], v[118:119], v[18:19], v[88:89]
	v_pk_fma_f32 v[90:91], v[118:119], v[62:63], v[90:91]
	s_waitcnt lgkmcnt(2)
	v_mfma_f32_32x32x16_bf16 v[40:55], v[108:111], v[124:127], 0
	v_add_f32_dpp v92, v92, v92 quad_perm:[2,3,0,1] row_mask:0xf bank_mask:0xf bound_ctrl:1
	v_add_f32_e32 v99, v90, v91
	ds_read_b128 v[112:115], v128 offset:8160
	v_cndmask_b32_e64 v100, v98, v96, s[38:39]
	v_cndmask_b32_e64 v102, v96, v98, s[38:39]
	v_add_f32_dpp v92, v92, v92 row_half_mirror row_mask:0xf bank_mask:0xf bound_ctrl:1
	ds_read_b128 v[56:59], v105 offset:18176
	v_cndmask_b32_e64 v101, v99, v97, s[38:39]
	v_cndmask_b32_e64 v103, v97, v99, s[38:39]
	v_add_f32_dpp v92, v92, v92 row_mirror row_mask:0xf bank_mask:0xf bound_ctrl:1
	v_pk_fma_f32 v[116:117], v[12:13], v[92:93], v[86:87] op_sel_hi:[1,0,1]
	v_pk_fma_f32 v[118:119], v[14:15], v[92:93], v[88:89] op_sel_hi:[1,0,1]
	s_waitcnt lgkmcnt(3)
	v_pk_mul_f32 v[84:85], v[116:117], v[28:29]
	v_pk_mul_f32 v[86:87], v[80:81], v[24:25] op_sel:[1,0]
	v_pk_fma_f32 v[84:85], v[118:119], v[30:31], v[84:85]
	v_pk_mul_f32 v[88:89], v[80:81], v[26:27] op_sel:[1,0]
	v_add_f32_e32 v92, v84, v85
	v_pk_fma_f32 v[86:87], v[116:117], v[36:37], v[86:87]
	v_pk_mul_f32 v[90:91], v[116:117], v[0:1]
	v_add_f32_dpp v92, v92, v92 quad_perm:[1,0,3,2] row_mask:0xf bank_mask:0xf bound_ctrl:1
	v_pk_fma_f32 v[88:89], v[118:119], v[38:39], v[88:89]
	v_pk_fma_f32 v[90:91], v[118:119], v[2:3], v[90:91]
	s_waitcnt lgkmcnt(1)
	v_mfma_f32_32x32x16_bf16 v[60:75], v[112:115], v[124:127], 0
	v_add_f32_dpp v92, v92, v92 quad_perm:[2,3,0,1] row_mask:0xf bank_mask:0xf bound_ctrl:1
	v_add_f32_e32 v96, v90, v91
	ds_read_b128 v[108:111], v128 offset:8704
	v_add_f32_dpp v102, v102, v100 row_ror:8 row_mask:0xf bank_mask:0xf bound_ctrl:1
	v_add_f32_dpp v92, v92, v92 row_half_mirror row_mask:0xf bank_mask:0xf bound_ctrl:1
	ds_read_b128 v[76:79], v105 offset:19456
	v_add_f32_dpp v103, v103, v101 row_ror:8 row_mask:0xf bank_mask:0xf bound_ctrl:1
	v_add_f32_dpp v92, v92, v92 row_mirror row_mask:0xf bank_mask:0xf bound_ctrl:1
	v_cndmask_b32_e64 v104, v103, v102, s[40:41]
	v_cndmask_b32_e64 v102, v102, v103, s[40:41]
	v_pk_fma_f32 v[116:117], v[32:33], v[92:93], v[86:87] op_sel_hi:[1,0,1]
	v_pk_fma_f32 v[118:119], v[34:35], v[92:93], v[88:89] op_sel_hi:[1,0,1]
	s_waitcnt lgkmcnt(2)
	v_pk_mul_f32 v[84:85], v[116:117], v[48:49]
	v_pk_mul_f32 v[86:87], v[82:83], v[44:45] op_sel_hi:[0,1]
	v_pk_fma_f32 v[84:85], v[118:119], v[50:51], v[84:85]
	v_pk_mul_f32 v[88:89], v[82:83], v[46:47] op_sel_hi:[0,1]
	v_add_f32_e32 v92, v84, v85
	v_pk_fma_f32 v[86:87], v[116:117], v[56:57], v[86:87]
	v_pk_mul_f32 v[90:91], v[116:117], v[20:21]
	v_add_f32_dpp v92, v92, v92 quad_perm:[1,0,3,2] row_mask:0xf bank_mask:0xf bound_ctrl:1
	v_pk_fma_f32 v[88:89], v[118:119], v[58:59], v[88:89]
	v_pk_fma_f32 v[90:91], v[118:119], v[22:23], v[90:91]
	s_waitcnt lgkmcnt(1)
	v_mfma_f32_32x32x16_bf16 v[0:15], v[108:111], v[124:127], 0
	v_add_f32_dpp v92, v92, v92 quad_perm:[2,3,0,1] row_mask:0xf bank_mask:0xf bound_ctrl:1
	v_add_f32_e32 v97, v90, v91
	ds_read_b128 v[112:115], v128 offset:9248
	v_add_f32_dpp v92, v92, v92 row_half_mirror row_mask:0xf bank_mask:0xf bound_ctrl:1
	ds_read_b128 v[16:19], v105 offset:20736
	v_add_f32_dpp v102, v102, v104 row_half_mirror row_mask:0xf bank_mask:0xf bound_ctrl:1
	v_add_f32_dpp v92, v92, v92 row_mirror row_mask:0xf bank_mask:0xf bound_ctrl:1
	v_pk_fma_f32 v[116:117], v[52:53], v[92:93], v[86:87] op_sel_hi:[1,0,1]
	v_pk_fma_f32 v[118:119], v[54:55], v[92:93], v[88:89] op_sel_hi:[1,0,1]
	v_add_f32_dpp v102, v102, v102 quad_perm:[1,0,3,2] row_mask:0xf bank_mask:0xf bound_ctrl:1
	s_waitcnt lgkmcnt(2)
	v_pk_mul_f32 v[84:85], v[116:117], v[68:69]
	v_pk_mul_f32 v[86:87], v[82:83], v[64:65] op_sel:[1,0]
	v_pk_fma_f32 v[84:85], v[118:119], v[70:71], v[84:85]
	v_pk_mul_f32 v[88:89], v[82:83], v[66:67] op_sel:[1,0]
	ds_read_b128 v[80:83], v106 offset:64
	v_add_f32_e32 v92, v84, v85
	v_pk_fma_f32 v[86:87], v[116:117], v[76:77], v[86:87]
	v_pk_mul_f32 v[90:91], v[116:117], v[40:41]
	v_add_f32_dpp v92, v92, v92 quad_perm:[1,0,3,2] row_mask:0xf bank_mask:0xf bound_ctrl:1
	v_pk_fma_f32 v[88:89], v[118:119], v[78:79], v[88:89]
	v_pk_fma_f32 v[90:91], v[118:119], v[42:43], v[90:91]
	s_waitcnt lgkmcnt(2)
; #define YRED4(dst) { \
;           float a0 = b3 ? p2 : p0, a1 = b3 ? p3 : p1; const float s0 = b3 ? p0 : p2, s1 = b3 ? p1 : p3; \
;           a0 += dppf<0x128>(s0); a1 += dppf<0x128>(s1); \
;           float cc = b2 ? a1 : a0; const float dd = b2 ? a0 : a1; \
;           cc += dppf<0x141>(dd); cc += dppf<0xB1>(cc); cc += dppf<0x4E>(cc); dst = cc; }
; __device__ __forceinline__ void phase_scan(KP p) {
;     ...
;         for (int g = 0; g < 8; ++g) {
;           const int st = g * 4;
;           SLD(C, st + 2); vnext = *(const float4*)(vb4 + st + 4);
;           __builtin_amdgcn_sched_barrier(0);
;           if (g > 0) { float yv; YRED4(yv); yb[(st - 4) * 16] = yv; }
;           SCOMP(A, vcur.x, q0);
;           SLD(D, st + 3);
;           __builtin_amdgcn_sched_barrier(0);
;           SCOMP(B, vcur.y, q1);
;           SLD(A, st + 4);
;           __builtin_amdgcn_sched_barrier(0);
;           SCOMP(C, vcur.z, q2);
;           SLD(B, st + 5);
;           __builtin_amdgcn_sched_barrier(0);
;           SCOMP(D, vcur.w, q3);
;           vcur = vnext; p0 = q0; p1 = q1; p2 = q2; p3 = q3;
	v_mfma_f32_32x32x16_bf16 v[20:35], v[112:115], v[124:127], 0
	v_add_f32_dpp v92, v92, v92 quad_perm:[2,3,0,1] row_mask:0xf bank_mask:0xf bound_ctrl:1
	v_add_f32_e32 v98, v90, v91
	ds_read_b128 v[108:111], v128 offset:9792
	v_add_f32_dpp v92, v92, v92 row_half_mirror row_mask:0xf bank_mask:0xf bound_ctrl:1
	ds_read_b128 v[36:39], v105 offset:22016
	v_add_f32_dpp v102, v102, v102 quad_perm:[2,3,0,1] row_mask:0xf bank_mask:0xf bound_ctrl:1
	v_add_f32_dpp v92, v92, v92 row_mirror row_mask:0xf bank_mask:0xf bound_ctrl:1
	v_pk_fma_f32 v[116:117], v[72:73], v[92:93], v[86:87] op_sel_hi:[1,0,1]
	v_pk_fma_f32 v[118:119], v[74:75], v[92:93], v[88:89] op_sel_hi:[1,0,1]
	ds_write_b32 v107, v102 offset:512
	s_waitcnt lgkmcnt(3)
	v_pk_mul_f32 v[84:85], v[116:117], v[8:9]
	v_pk_mul_f32 v[86:87], v[80:81], v[4:5] op_sel_hi:[0,1]
	v_pk_fma_f32 v[84:85], v[118:119], v[10:11], v[84:85]
	v_pk_mul_f32 v[88:89], v[80:81], v[6:7] op_sel_hi:[0,1]
	v_add_f32_e32 v92, v84, v85
	v_pk_fma_f32 v[86:87], v[116:117], v[16:17], v[86:87]
	v_pk_mul_f32 v[90:91], v[116:117], v[60:61]
	v_add_f32_dpp v92, v92, v92 quad_perm:[1,0,3,2] row_mask:0xf bank_mask:0xf bound_ctrl:1
	v_pk_fma_f32 v[88:89], v[118:119], v[18:19], v[88:89]
	v_pk_fma_f32 v[90:91], v[118:119], v[62:63], v[90:91]
	s_waitcnt lgkmcnt(2)
	v_mfma_f32_32x32x16_bf16 v[40:55], v[108:111], v[124:127], 0
	v_add_f32_dpp v92, v92, v92 quad_perm:[2,3,0,1] row_mask:0xf bank_mask:0xf bound_ctrl:1
	v_add_f32_e32 v99, v90, v91
	ds_read_b128 v[112:115], v128 offset:10336
	v_cndmask_b32_e64 v100, v98, v96, s[38:39]
	v_cndmask_b32_e64 v102, v96, v98, s[38:39]
	v_add_f32_dpp v92, v92, v92 row_half_mirror row_mask:0xf bank_mask:0xf bound_ctrl:1
	ds_read_b128 v[56:59], v105 offset:23296
	v_cndmask_b32_e64 v101, v99, v97, s[38:39]
	v_cndmask_b32_e64 v103, v97, v99, s[38:39]
	v_add_f32_dpp v92, v92, v92 row_mirror row_mask:0xf bank_mask:0xf bound_ctrl:1
	v_pk_fma_f32 v[116:117], v[12:13], v[92:93], v[86:87] op_sel_hi:[1,0,1]
	v_pk_fma_f32 v[118:119], v[14:15], v[92:93], v[88:89] op_sel_hi:[1,0,1]
	s_waitcnt lgkmcnt(3)
	v_pk_mul_f32 v[84:85], v[116:117], v[28:29]
	v_pk_mul_f32 v[86:87], v[80:81], v[24:25] op_sel:[1,0]
	v_pk_fma_f32 v[84:85], v[118:119], v[30:31], v[84:85]
	v_pk_mul_f32 v[88:89], v[80:81], v[26:27] op_sel:[1,0]
	v_add_f32_e32 v92, v84, v85
	v_pk_fma_f32 v[86:87], v[116:117], v[36:37], v[86:87]
	v_pk_mul_f32 v[90:91], v[116:117], v[0:1]
	v_add_f32_dpp v92, v92, v92 quad_perm:[1,0,3,2] row_mask:0xf bank_mask:0xf bound_ctrl:1
	v_pk_fma_f32 v[88:89], v[118:119], v[38:39], v[88:89]
	v_pk_fma_f32 v[90:91], v[118:119], v[2:3], v[90:91]
	s_waitcnt lgkmcnt(1)
	v_mfma_f32_32x32x16_bf16 v[60:75], v[112:115], v[124:127], 0
	v_add_f32_dpp v92, v92, v92 quad_perm:[2,3,0,1] row_mask:0xf bank_mask:0xf bound_ctrl:1
	v_add_f32_e32 v96, v90, v91
	ds_read_b128 v[108:111], v128 offset:10880
	v_add_f32_dpp v102, v102, v100 row_ror:8 row_mask:0xf bank_mask:0xf bound_ctrl:1
	v_add_f32_dpp v92, v92, v92 row_half_mirror row_mask:0xf bank_mask:0xf bound_ctrl:1
	ds_read_b128 v[76:79], v105 offset:24576
	v_add_f32_dpp v103, v103, v101 row_ror:8 row_mask:0xf bank_mask:0xf bound_ctrl:1
	v_add_f32_dpp v92, v92, v92 row_mirror row_mask:0xf bank_mask:0xf bound_ctrl:1
	v_cndmask_b32_e64 v104, v103, v102, s[40:41]
	v_cndmask_b32_e64 v102, v102, v103, s[40:41]
	v_pk_fma_f32 v[116:117], v[32:33], v[92:93], v[86:87] op_sel_hi:[1,0,1]
	v_pk_fma_f32 v[118:119], v[34:35], v[92:93], v[88:89] op_sel_hi:[1,0,1]
	s_waitcnt lgkmcnt(2)
	v_pk_mul_f32 v[84:85], v[116:117], v[48:49]
	v_pk_mul_f32 v[86:87], v[82:83], v[44:45] op_sel_hi:[0,1]
	v_pk_fma_f32 v[84:85], v[118:119], v[50:51], v[84:85]
	v_pk_mul_f32 v[88:89], v[82:83], v[46:47] op_sel_hi:[0,1]
	v_add_f32_e32 v92, v84, v85
	v_pk_fma_f32 v[86:87], v[116:117], v[56:57], v[86:87]
	v_pk_mul_f32 v[90:91], v[116:117], v[20:21]
	v_add_f32_dpp v92, v92, v92 quad_perm:[1,0,3,2] row_mask:0xf bank_mask:0xf bound_ctrl:1
	v_pk_fma_f32 v[88:89], v[118:119], v[58:59], v[88:89]
	v_pk_fma_f32 v[90:91], v[118:119], v[22:23], v[90:91]
	s_waitcnt lgkmcnt(1)
	v_mfma_f32_32x32x16_bf16 v[0:15], v[108:111], v[124:127], 0
	v_add_f32_dpp v92, v92, v92 quad_perm:[2,3,0,1] row_mask:0xf bank_mask:0xf bound_ctrl:1
	v_add_f32_e32 v97, v90, v91
	ds_read_b128 v[112:115], v128 offset:11424
	v_add_f32_dpp v92, v92, v92 row_half_mirror row_mask:0xf bank_mask:0xf bound_ctrl:1
	ds_read_b128 v[16:19], v105 offset:25856
	v_add_f32_dpp v102, v102, v104 row_half_mirror row_mask:0xf bank_mask:0xf bound_ctrl:1
	v_add_f32_dpp v92, v92, v92 row_mirror row_mask:0xf bank_mask:0xf bound_ctrl:1
	v_pk_fma_f32 v[116:117], v[52:53], v[92:93], v[86:87] op_sel_hi:[1,0,1]
	v_pk_fma_f32 v[118:119], v[54:55], v[92:93], v[88:89] op_sel_hi:[1,0,1]
	v_add_f32_dpp v102, v102, v102 quad_perm:[1,0,3,2] row_mask:0xf bank_mask:0xf bound_ctrl:1
	s_waitcnt lgkmcnt(2)
	v_pk_mul_f32 v[84:85], v[116:117], v[68:69]
	v_pk_mul_f32 v[86:87], v[82:83], v[64:65] op_sel:[1,0]
	v_pk_fma_f32 v[84:85], v[118:119], v[70:71], v[84:85]
	v_pk_mul_f32 v[88:89], v[82:83], v[66:67] op_sel:[1,0]
	ds_read_b128 v[80:83], v106 offset:80
	v_add_f32_e32 v92, v84, v85
	v_pk_fma_f32 v[86:87], v[116:117], v[76:77], v[86:87]
	v_pk_mul_f32 v[90:91], v[116:117], v[40:41]
	v_add_f32_dpp v92, v92, v92 quad_perm:[1,0,3,2] row_mask:0xf bank_mask:0xf bound_ctrl:1
	v_pk_fma_f32 v[88:89], v[118:119], v[78:79], v[88:89]
	v_pk_fma_f32 v[90:91], v[118:119], v[42:43], v[90:91]
	s_waitcnt lgkmcnt(2)
; #define YRED4(dst) { \
;           float a0 = b3 ? p2 : p0, a1 = b3 ? p3 : p1; const float s0 = b3 ? p0 : p2, s1 = b3 ? p1 : p3; \
;           a0 += dppf<0x128>(s0); a1 += dppf<0x128>(s1); \
;           float cc = b2 ? a1 : a0; const float dd = b2 ? a0 : a1; \
;           cc += dppf<0x141>(dd); cc += dppf<0xB1>(cc); cc += dppf<0x4E>(cc); dst = cc; }
; __device__ __forceinline__ void phase_scan(KP p) {
;     ...
;         for (int g = 0; g < 8; ++g) {
;           const int st = g * 4;
;           SLD(C, st + 2); vnext = *(const float4*)(vb4 + st + 4);
;           __builtin_amdgcn_sched_barrier(0);
;           if (g > 0) { float yv; YRED4(yv); yb[(st - 4) * 16] = yv; }
;           SCOMP(A, vcur.x, q0);
;           SLD(D, st + 3);
;           __builtin_amdgcn_sched_barrier(0);
;           SCOMP(B, vcur.y, q1);
;           SLD(A, st + 4);
;           __builtin_amdgcn_sched_barrier(0);
;           SCOMP(C, vcur.z, q2);
;           SLD(B, st + 5);
;           __builtin_amdgcn_sched_barrier(0);
;           SCOMP(D, vcur.w, q3);
;           vcur = vnext; p0 = q0; p1 = q1; p2 = q2; p3 = q3;
	v_mfma_f32_32x32x16_bf16 v[20:35], v[112:115], v[124:127], 0
	v_add_f32_dpp v92, v92, v92 quad_perm:[2,3,0,1] row_mask:0xf bank_mask:0xf bound_ctrl:1
	v_add_f32_e32 v98, v90, v91
	ds_read_b128 v[108:111], v128 offset:11968
	v_add_f32_dpp v92, v92, v92 row_half_mirror row_mask:0xf bank_mask:0xf bound_ctrl:1
	ds_read_b128 v[36:39], v105 offset:27136
	v_add_f32_dpp v102, v102, v102 quad_perm:[2,3,0,1] row_mask:0xf bank_mask:0xf bound_ctrl:1
	v_add_f32_dpp v92, v92, v92 row_mirror row_mask:0xf bank_mask:0xf bound_ctrl:1
	v_pk_fma_f32 v[116:117], v[72:73], v[92:93], v[86:87] op_sel_hi:[1,0,1]
	v_pk_fma_f32 v[118:119], v[74:75], v[92:93], v[88:89] op_sel_hi:[1,0,1]
	ds_write_b32 v107, v102 offset:768
	s_waitcnt lgkmcnt(3)
	v_pk_mul_f32 v[84:85], v[116:117], v[8:9]
	v_pk_mul_f32 v[86:87], v[80:81], v[4:5] op_sel_hi:[0,1]
	v_pk_fma_f32 v[84:85], v[118:119], v[10:11], v[84:85]
	v_pk_mul_f32 v[88:89], v[80:81], v[6:7] op_sel_hi:[0,1]
	v_add_f32_e32 v92, v84, v85
	v_pk_fma_f32 v[86:87], v[116:117], v[16:17], v[86:87]
	v_pk_mul_f32 v[90:91], v[116:117], v[60:61]
	v_add_f32_dpp v92, v92, v92 quad_perm:[1,0,3,2] row_mask:0xf bank_mask:0xf bound_ctrl:1
	v_pk_fma_f32 v[88:89], v[118:119], v[18:19], v[88:89]
	v_pk_fma_f32 v[90:91], v[118:119], v[62:63], v[90:91]
	s_waitcnt lgkmcnt(2)
	v_mfma_f32_32x32x16_bf16 v[40:55], v[108:111], v[124:127], 0
	v_add_f32_dpp v92, v92, v92 quad_perm:[2,3,0,1] row_mask:0xf bank_mask:0xf bound_ctrl:1
	v_add_f32_e32 v99, v90, v91
	ds_read_b128 v[112:115], v128 offset:12512
	v_cndmask_b32_e64 v100, v98, v96, s[38:39]
	v_cndmask_b32_e64 v102, v96, v98, s[38:39]
	v_add_f32_dpp v92, v92, v92 row_half_mirror row_mask:0xf bank_mask:0xf bound_ctrl:1
	ds_read_b128 v[56:59], v105 offset:28416
	v_cndmask_b32_e64 v101, v99, v97, s[38:39]
	v_cndmask_b32_e64 v103, v97, v99, s[38:39]
	v_add_f32_dpp v92, v92, v92 row_mirror row_mask:0xf bank_mask:0xf bound_ctrl:1
	v_pk_fma_f32 v[116:117], v[12:13], v[92:93], v[86:87] op_sel_hi:[1,0,1]
	v_pk_fma_f32 v[118:119], v[14:15], v[92:93], v[88:89] op_sel_hi:[1,0,1]
	s_waitcnt lgkmcnt(3)
	v_pk_mul_f32 v[84:85], v[116:117], v[28:29]
	v_pk_mul_f32 v[86:87], v[80:81], v[24:25] op_sel:[1,0]
	v_pk_fma_f32 v[84:85], v[118:119], v[30:31], v[84:85]
	v_pk_mul_f32 v[88:89], v[80:81], v[26:27] op_sel:[1,0]
	v_add_f32_e32 v92, v84, v85
	v_pk_fma_f32 v[86:87], v[116:117], v[36:37], v[86:87]
	v_pk_mul_f32 v[90:91], v[116:117], v[0:1]
	v_add_f32_dpp v92, v92, v92 quad_perm:[1,0,3,2] row_mask:0xf bank_mask:0xf bound_ctrl:1
	v_pk_fma_f32 v[88:89], v[118:119], v[38:39], v[88:89]
	v_pk_fma_f32 v[90:91], v[118:119], v[2:3], v[90:91]
	s_waitcnt lgkmcnt(1)
	v_mfma_f32_32x32x16_bf16 v[60:75], v[112:115], v[124:127], 0
	v_add_f32_dpp v92, v92, v92 quad_perm:[2,3,0,1] row_mask:0xf bank_mask:0xf bound_ctrl:1
	v_add_f32_e32 v96, v90, v91
	ds_read_b128 v[108:111], v128 offset:13056
	v_add_f32_dpp v102, v102, v100 row_ror:8 row_mask:0xf bank_mask:0xf bound_ctrl:1
	v_add_f32_dpp v92, v92, v92 row_half_mirror row_mask:0xf bank_mask:0xf bound_ctrl:1
	ds_read_b128 v[76:79], v105 offset:29696
	v_add_f32_dpp v103, v103, v101 row_ror:8 row_mask:0xf bank_mask:0xf bound_ctrl:1
	v_add_f32_dpp v92, v92, v92 row_mirror row_mask:0xf bank_mask:0xf bound_ctrl:1
	v_cndmask_b32_e64 v104, v103, v102, s[40:41]
	v_cndmask_b32_e64 v102, v102, v103, s[40:41]
	v_pk_fma_f32 v[116:117], v[32:33], v[92:93], v[86:87] op_sel_hi:[1,0,1]
	v_pk_fma_f32 v[118:119], v[34:35], v[92:93], v[88:89] op_sel_hi:[1,0,1]
	s_waitcnt lgkmcnt(2)
	v_pk_mul_f32 v[84:85], v[116:117], v[48:49]
	v_pk_mul_f32 v[86:87], v[82:83], v[44:45] op_sel_hi:[0,1]
	v_pk_fma_f32 v[84:85], v[118:119], v[50:51], v[84:85]
	v_pk_mul_f32 v[88:89], v[82:83], v[46:47] op_sel_hi:[0,1]
	v_add_f32_e32 v92, v84, v85
	v_pk_fma_f32 v[86:87], v[116:117], v[56:57], v[86:87]
	v_pk_mul_f32 v[90:91], v[116:117], v[20:21]
	v_add_f32_dpp v92, v92, v92 quad_perm:[1,0,3,2] row_mask:0xf bank_mask:0xf bound_ctrl:1
	v_pk_fma_f32 v[88:89], v[118:119], v[58:59], v[88:89]
	v_pk_fma_f32 v[90:91], v[118:119], v[22:23], v[90:91]
	s_waitcnt lgkmcnt(1)
	v_mfma_f32_32x32x16_bf16 v[0:15], v[108:111], v[124:127], 0
	v_add_f32_dpp v92, v92, v92 quad_perm:[2,3,0,1] row_mask:0xf bank_mask:0xf bound_ctrl:1
	v_add_f32_e32 v97, v90, v91
	ds_read_b128 v[112:115], v128 offset:13600
	v_add_f32_dpp v92, v92, v92 row_half_mirror row_mask:0xf bank_mask:0xf bound_ctrl:1
	ds_read_b128 v[16:19], v105 offset:30976
	v_add_f32_dpp v102, v102, v104 row_half_mirror row_mask:0xf bank_mask:0xf bound_ctrl:1
	v_add_f32_dpp v92, v92, v92 row_mirror row_mask:0xf bank_mask:0xf bound_ctrl:1
	v_pk_fma_f32 v[116:117], v[52:53], v[92:93], v[86:87] op_sel_hi:[1,0,1]
	v_pk_fma_f32 v[118:119], v[54:55], v[92:93], v[88:89] op_sel_hi:[1,0,1]
	v_add_f32_dpp v102, v102, v102 quad_perm:[1,0,3,2] row_mask:0xf bank_mask:0xf bound_ctrl:1
	s_waitcnt lgkmcnt(2)
	v_pk_mul_f32 v[84:85], v[116:117], v[68:69]
	v_pk_mul_f32 v[86:87], v[82:83], v[64:65] op_sel:[1,0]
	v_pk_fma_f32 v[84:85], v[118:119], v[70:71], v[84:85]
	v_pk_mul_f32 v[88:89], v[82:83], v[66:67] op_sel:[1,0]
	ds_read_b128 v[80:83], v106 offset:96
	v_add_f32_e32 v92, v84, v85
	v_pk_fma_f32 v[86:87], v[116:117], v[76:77], v[86:87]
	v_pk_mul_f32 v[90:91], v[116:117], v[40:41]
	v_add_f32_dpp v92, v92, v92 quad_perm:[1,0,3,2] row_mask:0xf bank_mask:0xf bound_ctrl:1
	v_pk_fma_f32 v[88:89], v[118:119], v[78:79], v[88:89]
	v_pk_fma_f32 v[90:91], v[118:119], v[42:43], v[90:91]
	s_waitcnt lgkmcnt(2)
; #define YRED4(dst) { \
;           float a0 = b3 ? p2 : p0, a1 = b3 ? p3 : p1; const float s0 = b3 ? p0 : p2, s1 = b3 ? p1 : p3; \
;           a0 += dppf<0x128>(s0); a1 += dppf<0x128>(s1); \
;           float cc = b2 ? a1 : a0; const float dd = b2 ? a0 : a1; \
;           cc += dppf<0x141>(dd); cc += dppf<0xB1>(cc); cc += dppf<0x4E>(cc); dst = cc; }
; __device__ __forceinline__ void phase_scan(KP p) {
;     ...
;         for (int g = 0; g < 8; ++g) {
;           const int st = g * 4;
;           SLD(C, st + 2); vnext = *(const float4*)(vb4 + st + 4);
;           __builtin_amdgcn_sched_barrier(0);
;           if (g > 0) { float yv; YRED4(yv); yb[(st - 4) * 16] = yv; }
;           SCOMP(A, vcur.x, q0);
;           SLD(D, st + 3);
;           __builtin_amdgcn_sched_barrier(0);
;           SCOMP(B, vcur.y, q1);
;           SLD(A, st + 4);
;           __builtin_amdgcn_sched_barrier(0);
;           SCOMP(C, vcur.z, q2);
;           SLD(B, st + 5);
;           __builtin_amdgcn_sched_barrier(0);
;           SCOMP(D, vcur.w, q3);
;           vcur = vnext; p0 = q0; p1 = q1; p2 = q2; p3 = q3;
	v_mfma_f32_32x32x16_bf16 v[20:35], v[112:115], v[124:127], 0
	v_add_f32_dpp v92, v92, v92 quad_perm:[2,3,0,1] row_mask:0xf bank_mask:0xf bound_ctrl:1
	v_add_f32_e32 v98, v90, v91
	ds_read_b128 v[108:111], v128 offset:14144
	v_add_f32_dpp v92, v92, v92 row_half_mirror row_mask:0xf bank_mask:0xf bound_ctrl:1
	ds_read_b128 v[36:39], v105 offset:32256
	v_add_f32_dpp v102, v102, v102 quad_perm:[2,3,0,1] row_mask:0xf bank_mask:0xf bound_ctrl:1
	v_add_f32_dpp v92, v92, v92 row_mirror row_mask:0xf bank_mask:0xf bound_ctrl:1
	v_pk_fma_f32 v[116:117], v[72:73], v[92:93], v[86:87] op_sel_hi:[1,0,1]
	v_pk_fma_f32 v[118:119], v[74:75], v[92:93], v[88:89] op_sel_hi:[1,0,1]
	ds_write_b32 v107, v102 offset:1024
	s_waitcnt lgkmcnt(3)
	v_pk_mul_f32 v[84:85], v[116:117], v[8:9]
	v_pk_mul_f32 v[86:87], v[80:81], v[4:5] op_sel_hi:[0,1]
	v_pk_fma_f32 v[84:85], v[118:119], v[10:11], v[84:85]
	v_pk_mul_f32 v[88:89], v[80:81], v[6:7] op_sel_hi:[0,1]
	v_add_f32_e32 v92, v84, v85
	v_pk_fma_f32 v[86:87], v[116:117], v[16:17], v[86:87]
	v_pk_mul_f32 v[90:91], v[116:117], v[60:61]
	v_add_f32_dpp v92, v92, v92 quad_perm:[1,0,3,2] row_mask:0xf bank_mask:0xf bound_ctrl:1
	v_pk_fma_f32 v[88:89], v[118:119], v[18:19], v[88:89]
	v_pk_fma_f32 v[90:91], v[118:119], v[62:63], v[90:91]
	s_waitcnt lgkmcnt(2)
	v_mfma_f32_32x32x16_bf16 v[40:55], v[108:111], v[124:127], 0
	v_add_f32_dpp v92, v92, v92 quad_perm:[2,3,0,1] row_mask:0xf bank_mask:0xf bound_ctrl:1
	v_add_f32_e32 v99, v90, v91
	ds_read_b128 v[112:115], v128 offset:14688
	v_cndmask_b32_e64 v100, v98, v96, s[38:39]
	v_cndmask_b32_e64 v102, v96, v98, s[38:39]
	v_add_f32_dpp v92, v92, v92 row_half_mirror row_mask:0xf bank_mask:0xf bound_ctrl:1
	ds_read_b128 v[56:59], v105 offset:33536
	v_cndmask_b32_e64 v101, v99, v97, s[38:39]
	v_cndmask_b32_e64 v103, v97, v99, s[38:39]
	v_add_f32_dpp v92, v92, v92 row_mirror row_mask:0xf bank_mask:0xf bound_ctrl:1
	v_pk_fma_f32 v[116:117], v[12:13], v[92:93], v[86:87] op_sel_hi:[1,0,1]
	v_pk_fma_f32 v[118:119], v[14:15], v[92:93], v[88:89] op_sel_hi:[1,0,1]
	s_waitcnt lgkmcnt(3)
	v_pk_mul_f32 v[84:85], v[116:117], v[28:29]
	v_pk_mul_f32 v[86:87], v[80:81], v[24:25] op_sel:[1,0]
	v_pk_fma_f32 v[84:85], v[118:119], v[30:31], v[84:85]
	v_pk_mul_f32 v[88:89], v[80:81], v[26:27] op_sel:[1,0]
	v_add_f32_e32 v92, v84, v85
	v_pk_fma_f32 v[86:87], v[116:117], v[36:37], v[86:87]
	v_pk_mul_f32 v[90:91], v[116:117], v[0:1]
	v_add_f32_dpp v92, v92, v92 quad_perm:[1,0,3,2] row_mask:0xf bank_mask:0xf bound_ctrl:1
	v_pk_fma_f32 v[88:89], v[118:119], v[38:39], v[88:89]
	v_pk_fma_f32 v[90:91], v[118:119], v[2:3], v[90:91]
	s_waitcnt lgkmcnt(1)
	v_mfma_f32_32x32x16_bf16 v[60:75], v[112:115], v[124:127], 0
	v_add_f32_dpp v92, v92, v92 quad_perm:[2,3,0,1] row_mask:0xf bank_mask:0xf bound_ctrl:1
	v_add_f32_e32 v96, v90, v91
	ds_read_b128 v[108:111], v128 offset:15232
	v_add_f32_dpp v102, v102, v100 row_ror:8 row_mask:0xf bank_mask:0xf bound_ctrl:1
	v_add_f32_dpp v92, v92, v92 row_half_mirror row_mask:0xf bank_mask:0xf bound_ctrl:1
	ds_read_b128 v[76:79], v105 offset:34816
	v_add_f32_dpp v103, v103, v101 row_ror:8 row_mask:0xf bank_mask:0xf bound_ctrl:1
	v_add_f32_dpp v92, v92, v92 row_mirror row_mask:0xf bank_mask:0xf bound_ctrl:1
	v_cndmask_b32_e64 v104, v103, v102, s[40:41]
	v_cndmask_b32_e64 v102, v102, v103, s[40:41]
	v_pk_fma_f32 v[116:117], v[32:33], v[92:93], v[86:87] op_sel_hi:[1,0,1]
	v_pk_fma_f32 v[118:119], v[34:35], v[92:93], v[88:89] op_sel_hi:[1,0,1]
	s_waitcnt lgkmcnt(2)
	v_pk_mul_f32 v[84:85], v[116:117], v[48:49]
	v_pk_mul_f32 v[86:87], v[82:83], v[44:45] op_sel_hi:[0,1]
	v_pk_fma_f32 v[84:85], v[118:119], v[50:51], v[84:85]
	v_pk_mul_f32 v[88:89], v[82:83], v[46:47] op_sel_hi:[0,1]
	v_add_f32_e32 v92, v84, v85
	v_pk_fma_f32 v[86:87], v[116:117], v[56:57], v[86:87]
	v_pk_mul_f32 v[90:91], v[116:117], v[20:21]
	v_add_f32_dpp v92, v92, v92 quad_perm:[1,0,3,2] row_mask:0xf bank_mask:0xf bound_ctrl:1
	v_pk_fma_f32 v[88:89], v[118:119], v[58:59], v[88:89]
	v_pk_fma_f32 v[90:91], v[118:119], v[22:23], v[90:91]
	s_waitcnt lgkmcnt(1)
	v_mfma_f32_32x32x16_bf16 v[0:15], v[108:111], v[124:127], 0
	v_add_f32_dpp v92, v92, v92 quad_perm:[2,3,0,1] row_mask:0xf bank_mask:0xf bound_ctrl:1
	v_add_f32_e32 v97, v90, v91
	ds_read_b128 v[112:115], v128 offset:15776
	v_add_f32_dpp v92, v92, v92 row_half_mirror row_mask:0xf bank_mask:0xf bound_ctrl:1
	ds_read_b128 v[16:19], v105 offset:36096
	v_add_f32_dpp v102, v102, v104 row_half_mirror row_mask:0xf bank_mask:0xf bound_ctrl:1
	v_add_f32_dpp v92, v92, v92 row_mirror row_mask:0xf bank_mask:0xf bound_ctrl:1
	v_pk_fma_f32 v[116:117], v[52:53], v[92:93], v[86:87] op_sel_hi:[1,0,1]
	v_pk_fma_f32 v[118:119], v[54:55], v[92:93], v[88:89] op_sel_hi:[1,0,1]
	v_add_f32_dpp v102, v102, v102 quad_perm:[1,0,3,2] row_mask:0xf bank_mask:0xf bound_ctrl:1
	s_waitcnt lgkmcnt(2)
	v_pk_mul_f32 v[84:85], v[116:117], v[68:69]
	v_pk_mul_f32 v[86:87], v[82:83], v[64:65] op_sel:[1,0]
	v_pk_fma_f32 v[84:85], v[118:119], v[70:71], v[84:85]
	v_pk_mul_f32 v[88:89], v[82:83], v[66:67] op_sel:[1,0]
	ds_read_b128 v[80:83], v106 offset:112
	v_add_f32_e32 v92, v84, v85
	v_pk_fma_f32 v[86:87], v[116:117], v[76:77], v[86:87]
	v_pk_mul_f32 v[90:91], v[116:117], v[40:41]
	v_add_f32_dpp v92, v92, v92 quad_perm:[1,0,3,2] row_mask:0xf bank_mask:0xf bound_ctrl:1
	v_pk_fma_f32 v[88:89], v[118:119], v[78:79], v[88:89]
	v_pk_fma_f32 v[90:91], v[118:119], v[42:43], v[90:91]
	s_waitcnt lgkmcnt(2)
; #define YRED4(dst) { \
;           float a0 = b3 ? p2 : p0, a1 = b3 ? p3 : p1; const float s0 = b3 ? p0 : p2, s1 = b3 ? p1 : p3; \
;           a0 += dppf<0x128>(s0); a1 += dppf<0x128>(s1); \
;           float cc = b2 ? a1 : a0; const float dd = b2 ? a0 : a1; \
;           cc += dppf<0x141>(dd); cc += dppf<0xB1>(cc); cc += dppf<0x4E>(cc); dst = cc; }
; __device__ __forceinline__ void phase_scan(KP p) {
;     ...
;         for (int g = 0; g < 8; ++g) {
;           const int st = g * 4;
;           SLD(C, st + 2); vnext = *(const float4*)(vb4 + st + 4);
;           __builtin_amdgcn_sched_barrier(0);
;           if (g > 0) { float yv; YRED4(yv); yb[(st - 4) * 16] = yv; }
;           SCOMP(A, vcur.x, q0);
;           SLD(D, st + 3);
;           __builtin_amdgcn_sched_barrier(0);
;           SCOMP(B, vcur.y, q1);
;           SLD(A, st + 4);
;           __builtin_amdgcn_sched_barrier(0);
;           SCOMP(C, vcur.z, q2);
;           SLD(B, st + 5);
;           __builtin_amdgcn_sched_barrier(0);
;           SCOMP(D, vcur.w, q3);
;           vcur = vnext; p0 = q0; p1 = q1; p2 = q2; p3 = q3;
;         }
;         { float yv; YRED4(yv); yb[28 * 16] = yv; }
	v_mfma_f32_32x32x16_bf16 v[20:35], v[112:115], v[124:127], 0
	v_add_f32_dpp v92, v92, v92 quad_perm:[2,3,0,1] row_mask:0xf bank_mask:0xf bound_ctrl:1
	v_add_f32_e32 v98, v90, v91
	ds_read_b128 v[108:111], v128 offset:16320
	v_add_f32_dpp v92, v92, v92 row_half_mirror row_mask:0xf bank_mask:0xf bound_ctrl:1
	ds_read_b128 v[36:39], v105 offset:37376
	v_add_f32_dpp v102, v102, v102 quad_perm:[2,3,0,1] row_mask:0xf bank_mask:0xf bound_ctrl:1
	v_add_f32_dpp v92, v92, v92 row_mirror row_mask:0xf bank_mask:0xf bound_ctrl:1
	v_pk_fma_f32 v[116:117], v[72:73], v[92:93], v[86:87] op_sel_hi:[1,0,1]
	v_pk_fma_f32 v[118:119], v[74:75], v[92:93], v[88:89] op_sel_hi:[1,0,1]
	ds_write_b32 v107, v102 offset:1280
	s_waitcnt lgkmcnt(3)
	v_pk_mul_f32 v[84:85], v[116:117], v[8:9]
	v_pk_mul_f32 v[86:87], v[80:81], v[4:5] op_sel_hi:[0,1]
	v_pk_fma_f32 v[84:85], v[118:119], v[10:11], v[84:85]
	v_pk_mul_f32 v[88:89], v[80:81], v[6:7] op_sel_hi:[0,1]
	v_add_f32_e32 v92, v84, v85
	v_pk_fma_f32 v[86:87], v[116:117], v[16:17], v[86:87]
	v_pk_mul_f32 v[90:91], v[116:117], v[60:61]
	v_add_f32_dpp v92, v92, v92 quad_perm:[1,0,3,2] row_mask:0xf bank_mask:0xf bound_ctrl:1
	v_pk_fma_f32 v[88:89], v[118:119], v[18:19], v[88:89]
	v_pk_fma_f32 v[90:91], v[118:119], v[62:63], v[90:91]
	s_waitcnt lgkmcnt(2)
	v_mfma_f32_32x32x16_bf16 v[40:55], v[108:111], v[124:127], 0
	v_add_f32_dpp v92, v92, v92 quad_perm:[2,3,0,1] row_mask:0xf bank_mask:0xf bound_ctrl:1
	v_add_f32_e32 v99, v90, v91
	ds_read_b128 v[112:115], v128 offset:16864
	v_cndmask_b32_e64 v100, v98, v96, s[38:39]
	v_cndmask_b32_e64 v102, v96, v98, s[38:39]
	v_add_f32_dpp v92, v92, v92 row_half_mirror row_mask:0xf bank_mask:0xf bound_ctrl:1
	ds_read_b128 v[56:59], v105 offset:38656
	v_cndmask_b32_e64 v101, v99, v97, s[38:39]
	v_cndmask_b32_e64 v103, v97, v99, s[38:39]
	v_add_f32_dpp v92, v92, v92 row_mirror row_mask:0xf bank_mask:0xf bound_ctrl:1
	v_pk_fma_f32 v[116:117], v[12:13], v[92:93], v[86:87] op_sel_hi:[1,0,1]
	v_pk_fma_f32 v[118:119], v[14:15], v[92:93], v[88:89] op_sel_hi:[1,0,1]
	s_waitcnt lgkmcnt(3)
	v_pk_mul_f32 v[84:85], v[116:117], v[28:29]
	v_pk_mul_f32 v[86:87], v[80:81], v[24:25] op_sel:[1,0]
	v_pk_fma_f32 v[84:85], v[118:119], v[30:31], v[84:85]
	v_pk_mul_f32 v[88:89], v[80:81], v[26:27] op_sel:[1,0]
	v_add_f32_e32 v92, v84, v85
	v_pk_fma_f32 v[86:87], v[116:117], v[36:37], v[86:87]
	v_pk_mul_f32 v[90:91], v[116:117], v[0:1]
	v_add_f32_dpp v92, v92, v92 quad_perm:[1,0,3,2] row_mask:0xf bank_mask:0xf bound_ctrl:1
	v_pk_fma_f32 v[88:89], v[118:119], v[38:39], v[88:89]
	v_pk_fma_f32 v[90:91], v[118:119], v[2:3], v[90:91]
	s_waitcnt lgkmcnt(1)
	v_mfma_f32_32x32x16_bf16 v[60:75], v[112:115], v[124:127], 0
	v_add_f32_dpp v92, v92, v92 quad_perm:[2,3,0,1] row_mask:0xf bank_mask:0xf bound_ctrl:1
	v_add_f32_e32 v96, v90, v91
	v_add_f32_dpp v102, v102, v100 row_ror:8 row_mask:0xf bank_mask:0xf bound_ctrl:1
	v_add_f32_dpp v92, v92, v92 row_half_mirror row_mask:0xf bank_mask:0xf bound_ctrl:1
	ds_read_b128 v[76:79], v105 offset:39936
	v_add_f32_dpp v103, v103, v101 row_ror:8 row_mask:0xf bank_mask:0xf bound_ctrl:1
	v_add_f32_dpp v92, v92, v92 row_mirror row_mask:0xf bank_mask:0xf bound_ctrl:1
	v_cndmask_b32_e64 v104, v103, v102, s[40:41]
	v_cndmask_b32_e64 v102, v102, v103, s[40:41]
	v_pk_fma_f32 v[116:117], v[32:33], v[92:93], v[86:87] op_sel_hi:[1,0,1]
	v_pk_fma_f32 v[118:119], v[34:35], v[92:93], v[88:89] op_sel_hi:[1,0,1]
	s_waitcnt lgkmcnt(1)
	v_pk_mul_f32 v[84:85], v[116:117], v[48:49]
	v_pk_mul_f32 v[86:87], v[82:83], v[44:45] op_sel_hi:[0,1]
	v_pk_fma_f32 v[84:85], v[118:119], v[50:51], v[84:85]
	v_pk_mul_f32 v[88:89], v[82:83], v[46:47] op_sel_hi:[0,1]
	v_add_f32_e32 v92, v84, v85
	v_pk_fma_f32 v[86:87], v[116:117], v[56:57], v[86:87]
	v_pk_mul_f32 v[90:91], v[116:117], v[20:21]
	v_add_f32_dpp v92, v92, v92 quad_perm:[1,0,3,2] row_mask:0xf bank_mask:0xf bound_ctrl:1
	v_pk_fma_f32 v[88:89], v[118:119], v[58:59], v[88:89]
	v_pk_fma_f32 v[90:91], v[118:119], v[22:23], v[90:91]
	v_add_f32_dpp v92, v92, v92 quad_perm:[2,3,0,1] row_mask:0xf bank_mask:0xf bound_ctrl:1
	v_add_f32_e32 v97, v90, v91
	s_nop 0
	v_add_f32_dpp v92, v92, v92 row_half_mirror row_mask:0xf bank_mask:0xf bound_ctrl:1
	v_add_f32_dpp v102, v102, v104 row_half_mirror row_mask:0xf bank_mask:0xf bound_ctrl:1
	s_nop 0
	v_add_f32_dpp v92, v92, v92 row_mirror row_mask:0xf bank_mask:0xf bound_ctrl:1
	v_pk_fma_f32 v[116:117], v[52:53], v[92:93], v[86:87] op_sel_hi:[1,0,1]
	v_pk_fma_f32 v[118:119], v[54:55], v[92:93], v[88:89] op_sel_hi:[1,0,1]
	v_add_f32_dpp v102, v102, v102 quad_perm:[1,0,3,2] row_mask:0xf bank_mask:0xf bound_ctrl:1
	s_waitcnt lgkmcnt(0)
	v_pk_mul_f32 v[84:85], v[116:117], v[68:69]
	v_pk_mul_f32 v[86:87], v[82:83], v[64:65] op_sel:[1,0]
	v_pk_fma_f32 v[84:85], v[118:119], v[70:71], v[84:85]
	v_pk_mul_f32 v[88:89], v[82:83], v[66:67] op_sel:[1,0]
	v_add_f32_e32 v92, v84, v85
	v_pk_fma_f32 v[86:87], v[116:117], v[76:77], v[86:87]
	v_pk_mul_f32 v[90:91], v[116:117], v[40:41]
	v_add_f32_dpp v92, v92, v92 quad_perm:[1,0,3,2] row_mask:0xf bank_mask:0xf bound_ctrl:1
	v_pk_fma_f32 v[88:89], v[118:119], v[78:79], v[88:89]
	v_pk_fma_f32 v[90:91], v[118:119], v[42:43], v[90:91]
	v_add_f32_dpp v92, v92, v92 quad_perm:[2,3,0,1] row_mask:0xf bank_mask:0xf bound_ctrl:1
	v_add_f32_e32 v98, v90, v91
	s_nop 0
	v_add_f32_dpp v92, v92, v92 row_half_mirror row_mask:0xf bank_mask:0xf bound_ctrl:1
	v_add_f32_dpp v102, v102, v102 quad_perm:[2,3,0,1] row_mask:0xf bank_mask:0xf bound_ctrl:1
	s_nop 0
	v_add_f32_dpp v92, v92, v92 row_mirror row_mask:0xf bank_mask:0xf bound_ctrl:1
	v_pk_fma_f32 v[116:117], v[72:73], v[92:93], v[86:87] op_sel_hi:[1,0,1]
	v_pk_fma_f32 v[118:119], v[74:75], v[92:93], v[88:89] op_sel_hi:[1,0,1]
	ds_write_b32 v107, v102 offset:1536
	v_cndmask_b32_e64 v100, v98, v96, s[38:39]
	v_pk_mul_f32 v[90:91], v[116:117], v[60:61]
	v_cndmask_b32_e64 v102, v96, v98, s[38:39]
	v_pk_fma_f32 v[90:91], v[118:119], v[62:63], v[90:91]
	s_nop 0
	v_add_f32_e32 v99, v90, v91
	v_add_f32_dpp v102, v102, v100 row_ror:8 row_mask:0xf bank_mask:0xf bound_ctrl:1
	v_cndmask_b32_e64 v101, v99, v97, s[38:39]
	v_cndmask_b32_e64 v103, v97, v99, s[38:39]
	s_nop 1
	v_add_f32_dpp v103, v103, v101 row_ror:8 row_mask:0xf bank_mask:0xf bound_ctrl:1
	v_cndmask_b32_e64 v104, v103, v102, s[40:41]
	v_cndmask_b32_e64 v102, v102, v103, s[40:41]
	s_nop 1
	v_add_f32_dpp v102, v102, v104 row_half_mirror row_mask:0xf bank_mask:0xf bound_ctrl:1
	s_nop 1
	v_add_f32_dpp v102, v102, v102 quad_perm:[1,0,3,2] row_mask:0xf bank_mask:0xf bound_ctrl:1
	s_nop 1
	v_add_f32_dpp v102, v102, v102 quad_perm:[2,3,0,1] row_mask:0xf bank_mask:0xf bound_ctrl:1
	ds_write_b32 v107, v102 offset:1792
	s_xor_b32 s19, s70, 1
	s_mul_i32 s74, s19, 0x4400
	v_add_u32_e32 v128, s74, v129
	s_mul_i32 s74, s19, 0xa000
	v_lshl_add_u32 v106, s19, 11, v121
	v_add_u32_e32 v105, s74, v120
	v_lshl_add_u32 v107, s19, 11, v146
	s_branch .LBB0_755
